# attention: next tile's first K-fragment LDS reads issued in the last P.V gaps, before the closing barrier (each wave waits its DMA one tile early, vmcnt(0))
# speedup vs baseline: 1.0058x; 1.0003x over previous
.LBB0_106:
	v_mov_b32_e32 v14, v0
	v_mov_b32_e32 v15, v0
	s_waitcnt vmcnt(0) lgkmcnt(0)
	s_barrier
	v_mov_b32_e32 v1, v0
	v_mov_b32_e32 v2, v0
	v_mov_b32_e32 v3, v0
	v_mov_b32_e32 v4, v0
	v_mov_b32_e32 v5, v0
	v_mov_b32_e32 v6, v0
	v_mov_b32_e32 v7, v0
	v_mov_b32_e32 v8, v0
	v_mov_b32_e32 v9, v0
	v_mov_b32_e32 v10, v0
	v_mov_b32_e32 v11, v0
	v_mov_b32_e32 v12, v0
	v_mov_b32_e32 v13, v0
	s_lshl_b32 s30, s43, 12
	s_lshl_b32 s44, s48, 7
	v_mov_b64_e32 v[62:63], v[14:15]
	v_mov_b64_e32 v[46:47], v[14:15]
	v_mov_b64_e32 v[30:31], v[14:15]
	s_add_i32 s43, s30, 0xffffff80
	v_add_u32_e32 v153, s44, v171
	v_add_u32_e32 v155, s44, v172
	s_add_i32 s45, s46, 0x80
	s_mov_b32 s50, 2
	s_mov_b32 s51, 1
	s_mov_b32 s53, 0
	v_mov_b32_e32 v157, 0
	v_mov_b32_e32 v159, 0
	v_mov_b32_e32 v96, 0
	v_mov_b32_e32 v97, 0
	v_mov_b32_e32 v98, 0
	v_mov_b32_e32 v99, 0
	v_mov_b32_e32 v100, 0
	v_mov_b32_e32 v101, 0
	v_mov_b32_e32 v102, 0
	v_mov_b32_e32 v103, 0
	v_mov_b32_e32 v104, 0
	v_mov_b32_e32 v105, 0
	v_mov_b32_e32 v106, 0
	v_mov_b32_e32 v107, 0
	v_mov_b32_e32 v108, 0
	v_mov_b32_e32 v109, 0
	v_mov_b32_e32 v110, 0
	v_mov_b32_e32 v111, 0
	v_mov_b64_e32 v[60:61], v[12:13]
	v_mov_b64_e32 v[58:59], v[10:11]
	v_mov_b64_e32 v[56:57], v[8:9]
	v_mov_b64_e32 v[54:55], v[6:7]
	v_mov_b64_e32 v[52:53], v[4:5]
	v_mov_b64_e32 v[50:51], v[2:3]
	v_mov_b64_e32 v[48:49], v[0:1]
	v_mov_b64_e32 v[44:45], v[12:13]
	v_mov_b64_e32 v[42:43], v[10:11]
	v_mov_b64_e32 v[40:41], v[8:9]
	v_mov_b64_e32 v[38:39], v[6:7]
	v_mov_b64_e32 v[36:37], v[4:5]
	v_mov_b64_e32 v[34:35], v[2:3]
	v_mov_b64_e32 v[32:33], v[0:1]
	v_mov_b64_e32 v[28:29], v[12:13]
	v_mov_b64_e32 v[26:27], v[10:11]
	v_mov_b64_e32 v[24:25], v[8:9]
	v_mov_b64_e32 v[22:23], v[6:7]
	v_mov_b64_e32 v[20:21], v[4:5]
	v_mov_b64_e32 v[18:19], v[2:3]
	v_mov_b64_e32 v[16:17], v[0:1]
	s_mov_b32 s52, 0
	s_waitcnt vmcnt(0)
	s_mul_i32 s30, s53, 0x2400
	v_add_u32_e32 v242, s30, v173
	s_mul_i32 s30, s53, 0x4800
	v_add_u32_e32 v243, s30, v174
	s_barrier
	ds_read_b128 v[112:115], v242 offset:0
	ds_read_b128 v[116:119], v242 offset:32
	ds_read_b128 v[120:123], v242 offset:64
	ds_read_b128 v[124:127], v242 offset:96
	s_waitcnt lgkmcnt(0)
	v_readfirstlane_b32 s30, v191
	s_lshr_b32 s30, s30, 8
	s_cmp_eq_u32 s30, 0
	s_cbranch_scc1 .Latt_diff_p0
	s_setprio 1
.Latt_diff_p0:
.LBB0_107:
.LBB0_116:
	s_add_i32 s30, s52, 2
	s_cmp_ge_u32 s30, s21
	s_cselect_b64 s[46:47], -1, 0
	s_cbranch_scc1 .Latt_diff_dmaend
	s_cmp_lt_u32 s52, 2
	s_cselect_b32 s48, s45, s43
	s_mul_i32 s55, s50, 0x2400
	s_add_i32 s56, s55, s41
	s_mov_b32 m0, s56
	v_lshl_add_u32 v244, s48, 12, v153
	global_load_lds_dwordx4 v244, s[18:19]
	s_ashr_i32 s49, s48, 31
	s_lshl_b64 s[30:31], s[48:49], 1
	s_add_i32 s55, s55, s56
	s_add_i32 m0, s55, 0x6c00
	s_add_u32 s30, s39, s30
	s_addc_u32 s31, s42, s31
	global_load_lds_dwordx4 v150, s[30:31]
	s_add_i32 m0, s55, 0x8c00
	s_and_b64 vcc, exec, s[14:15]
	global_load_lds_dwordx4 v148, s[30:31]
	s_cbranch_vccz .Latt_diff_dmax
.Latt_diff_dmaend:
	v_mfma_f32_32x32x16_bf16 v[64:79], v[112:115], v[130:133], v[96:111]
	ds_read_b128 v[112:115], v242 offset:4608
	v_mfma_f32_32x32x16_bf16 v[64:79], v[116:119], v[134:137], v[64:79]
	ds_read_b128 v[116:119], v242 offset:4640
	v_mfma_f32_32x32x16_bf16 v[64:79], v[120:123], v[138:141], v[64:79]
	ds_read_b128 v[120:123], v242 offset:4672
	v_mfma_f32_32x32x16_bf16 v[64:79], v[124:127], v[142:145], v[64:79]
	ds_read_b128 v[124:127], v242 offset:4704
	s_waitcnt lgkmcnt(2)
	v_mfma_f32_32x32x16_bf16 v[80:95], v[112:115], v[130:133], v[96:111]
	v_mfma_f32_32x32x16_bf16 v[80:95], v[116:119], v[134:137], v[80:95]
	s_waitcnt lgkmcnt(0)
	v_mfma_f32_32x32x16_bf16 v[80:95], v[120:123], v[138:141], v[80:95]
	v_mfma_f32_32x32x16_bf16 v[80:95], v[124:127], v[142:145], v[80:95]
	ds_read_b128 v[112:115], v243 offset:27648
	ds_read_b128 v[116:119], v243 offset:32256
	ds_read_b128 v[120:123], v243 offset:36864
	ds_read_b128 v[124:127], v243 offset:41472
	s_cmp_eq_u32 s52, 0
	s_cselect_b32 s31, 0xff7fffff, 0
	v_max3_f32 v227, v64, v65, v66
	v_max3_f32 v228, v67, v68, v69
	v_max3_f32 v227, v227, v70, v71
	v_max3_f32 v228, v228, v72, v73
	v_max3_f32 v227, v227, v74, v75
	v_max3_f32 v228, v228, v76, v77
	v_max3_f32 v227, v227, v78, v79
	v_max3_f32 v229, v80, v81, v82
	v_max3_f32 v226, v83, v84, v85
	v_max3_f32 v229, v229, v86, v87
	v_max3_f32 v226, v226, v88, v89
	v_max3_f32 v229, v229, v90, v91
	v_max3_f32 v226, v226, v92, v93
	v_max3_f32 v229, v229, v94, v95
	v_max3_f32 v226, v226, v227, v228
	v_max_f32_e32 v226, v226, v229
	v_cmp_lt_f32_e32 vcc, s58, v226
	s_cmp_eq_u32 s52, 0
	s_cbranch_scc1 .Latt_diff_rare
	s_cbranch_vccnz .Latt_diff_rare
.Latt_diff_norescale:
	v_exp_f32_e32 v64, v64
	v_exp_f32_e32 v65, v65
	v_exp_f32_e32 v66, v66
	v_exp_f32_e32 v67, v67
	v_exp_f32_e32 v68, v68
	v_exp_f32_e32 v69, v69
	v_exp_f32_e32 v70, v70
	v_exp_f32_e32 v71, v71
	v_cvt_pk_bf16_f32 v218, v64, v65
	v_cvt_pk_bf16_f32 v219, v66, v67
	v_cvt_pk_bf16_f32 v220, v68, v69
	v_cvt_pk_bf16_f32 v221, v70, v71
	s_waitcnt lgkmcnt(2)
	s_nop 0
	v_mfma_f32_32x32x16_bf16 v[0:15], v[112:115], v[218:221], v[0:15]
	ds_read_b128 v[112:115], v243 offset:27680
	v_exp_f32_e32 v72, v72
	v_exp_f32_e32 v73, v73
	v_exp_f32_e32 v74, v74
	v_exp_f32_e32 v75, v75
	v_mfma_f32_32x32x16_bf16 v[48:63], v[116:119], v[218:221], v[48:63]
	ds_read_b128 v[116:119], v243 offset:32288
	v_cvt_pk_bf16_f32 v222, v72, v73
	v_exp_f32_e32 v76, v76
	v_exp_f32_e32 v77, v77
	v_cvt_pk_bf16_f32 v223, v74, v75
	s_waitcnt lgkmcnt(2)
	v_mfma_f32_32x32x16_bf16 v[32:47], v[120:123], v[218:221], v[32:47]
	ds_read_b128 v[120:123], v243 offset:36896
	v_exp_f32_e32 v78, v78
	v_exp_f32_e32 v79, v79
	v_cvt_pk_bf16_f32 v224, v76, v77
	v_cvt_pk_bf16_f32 v225, v78, v79
	v_mfma_f32_32x32x16_bf16 v[16:31], v[124:127], v[218:221], v[16:31]
	ds_read_b128 v[124:127], v243 offset:41504
	v_add_f32_e32 v226, v64, v68
	v_add_f32_e32 v227, v65, v69
	v_add_f32_e32 v228, v66, v70
	v_add_f32_e32 v229, v67, v71
	s_waitcnt lgkmcnt(2)
	v_mfma_f32_32x32x16_bf16 v[0:15], v[112:115], v[222:225], v[0:15]
	ds_read_b128 v[112:115], v243 offset:27712
	v_exp_f32_e32 v80, v80
	v_exp_f32_e32 v81, v81
	v_exp_f32_e32 v82, v82
	v_exp_f32_e32 v83, v83
	v_cvt_pk_bf16_f32 v218, v80, v81
	v_mfma_f32_32x32x16_bf16 v[48:63], v[116:119], v[222:225], v[48:63]
	ds_read_b128 v[116:119], v243 offset:32320
	v_exp_f32_e32 v84, v84
	v_exp_f32_e32 v85, v85
	v_cvt_pk_bf16_f32 v219, v82, v83
	v_exp_f32_e32 v86, v86
	v_exp_f32_e32 v87, v87
	s_waitcnt lgkmcnt(2)
	v_mfma_f32_32x32x16_bf16 v[32:47], v[120:123], v[222:225], v[32:47]
	ds_read_b128 v[120:123], v243 offset:36928
	v_cvt_pk_bf16_f32 v220, v84, v85
	v_cvt_pk_bf16_f32 v221, v86, v87
	v_add_f32_e32 v226, v226, v72
	v_add_f32_e32 v227, v227, v73
	v_add_f32_e32 v228, v228, v74
	v_mfma_f32_32x32x16_bf16 v[16:31], v[124:127], v[222:225], v[16:31]
	ds_read_b128 v[124:127], v243 offset:41536
	v_add_f32_e32 v229, v229, v75
	v_add_f32_e32 v226, v226, v76
	v_add_f32_e32 v227, v227, v77
	v_add_f32_e32 v228, v228, v78
	v_add_f32_e32 v229, v229, v79
	s_waitcnt lgkmcnt(2)
	v_mfma_f32_32x32x16_bf16 v[0:15], v[112:115], v[218:221], v[0:15]
	ds_read_b128 v[112:115], v243 offset:27744
	v_exp_f32_e32 v88, v88
	v_exp_f32_e32 v89, v89
	v_exp_f32_e32 v90, v90
	v_exp_f32_e32 v91, v91
	v_cvt_pk_bf16_f32 v222, v88, v89
	v_mfma_f32_32x32x16_bf16 v[48:63], v[116:119], v[218:221], v[48:63]
	ds_read_b128 v[116:119], v243 offset:32352
	v_exp_f32_e32 v92, v92
	v_exp_f32_e32 v93, v93
	v_cvt_pk_bf16_f32 v223, v90, v91
	v_exp_f32_e32 v94, v94
	v_exp_f32_e32 v95, v95
	s_waitcnt lgkmcnt(2)
	v_mfma_f32_32x32x16_bf16 v[32:47], v[120:123], v[218:221], v[32:47]
	ds_read_b128 v[120:123], v243 offset:36960
	v_cvt_pk_bf16_f32 v224, v92, v93
	v_cvt_pk_bf16_f32 v225, v94, v95
	v_add_f32_e32 v226, v226, v80
	v_add_f32_e32 v227, v227, v81
	v_add_f32_e32 v228, v228, v82
	v_mfma_f32_32x32x16_bf16 v[16:31], v[124:127], v[218:221], v[16:31]
	ds_read_b128 v[124:127], v243 offset:41568
	v_add_f32_e32 v229, v229, v83
	v_add_f32_e32 v226, v226, v84
	v_add_f32_e32 v227, v227, v85
	v_add_f32_e32 v228, v228, v86
	v_add_f32_e32 v229, v229, v87
	s_waitcnt lgkmcnt(2)
	v_mfma_f32_32x32x16_bf16 v[0:15], v[112:115], v[222:225], v[0:15]
	s_mul_i32 s30, s51, 0x2400
	v_add_u32_e32 v242, s30, v173
	ds_read_b128 v[112:115], v242 offset:0
	v_add_f32_e32 v226, v226, v88
	v_add_f32_e32 v227, v227, v89
	v_mfma_f32_32x32x16_bf16 v[48:63], v[116:119], v[222:225], v[48:63]
	ds_read_b128 v[116:119], v242 offset:32
	v_add_f32_e32 v228, v228, v90
	v_add_f32_e32 v229, v229, v91
	s_waitcnt lgkmcnt(2)
	v_mfma_f32_32x32x16_bf16 v[32:47], v[120:123], v[222:225], v[32:47]
	ds_read_b128 v[120:123], v242 offset:64
	v_add_f32_e32 v226, v226, v92
	v_add_f32_e32 v227, v227, v93
	v_mfma_f32_32x32x16_bf16 v[16:31], v[124:127], v[222:225], v[16:31]
	ds_read_b128 v[124:127], v242 offset:96
	v_add_f32_e32 v228, v228, v94
	v_add_f32_e32 v229, v229, v95
	v_add_f32_e32 v226, v226, v227
	v_add_f32_e32 v228, v228, v229
	v_add_f32_e32 v226, v226, v228
	v_add_f32_e32 v157, v157, v226
.Latt_diff_skip:
	s_waitcnt vmcnt(0)
	s_add_i32 s30, s50, 1
	s_cmp_lg_u32 s50, 2
	s_cselect_b32 s46, s30, 0
	s_add_i32 s52, s52, 1
	s_add_i32 s43, s43, 64
	s_add_i32 s45, s45, 64
	s_mov_b32 s53, s51
	s_mov_b32 s51, s50
	s_mov_b32 s50, s46
	s_mul_i32 s30, s53, 0x4800
	v_add_u32_e32 v243, s30, v174
	s_cmp_eq_u32 s21, s52
	s_waitcnt lgkmcnt(0)
	s_barrier
	s_cbranch_scc0 .LBB0_107
	s_branch .LBB0_88

.LBB0_177:
	v_mov_b32_e32 v14, v0
	v_mov_b32_e32 v15, v0
	s_waitcnt vmcnt(0) lgkmcnt(0)
	s_barrier
	v_mov_b32_e32 v1, v0
	v_mov_b32_e32 v2, v0
	v_mov_b32_e32 v3, v0
	v_mov_b32_e32 v4, v0
	v_mov_b32_e32 v5, v0
	v_mov_b32_e32 v6, v0
	v_mov_b32_e32 v7, v0
	v_mov_b32_e32 v8, v0
	v_mov_b32_e32 v9, v0
	v_mov_b32_e32 v10, v0
	v_mov_b32_e32 v11, v0
	v_mov_b32_e32 v12, v0
	v_mov_b32_e32 v13, v0
	s_lshl_b32 s49, s49, 12
	v_mov_b64_e32 v[30:31], v[14:15]
	v_mov_b64_e32 v[46:47], v[14:15]
	v_mov_b64_e32 v[62:63], v[14:15]
	v_mad_u64_u32 v[222:223], s[30:31], s50, v238, v[190:191]
	v_mad_u64_u32 v[224:225], s[30:31], s50, v240, v[192:193]
	v_mad_u64_u32 v[226:227], s[30:31], s50, v242, v[194:195]
	v_mad_u64_u32 v[228:229], s[30:31], s50, v244, v[196:197]
	s_addk_i32 s49, 0xff80
	s_add_i32 s51, s60, 0x80
	s_mov_b32 s52, 2
	s_mov_b32 s53, 1
	s_mov_b32 s56, 0
	v_mov_b32_e32 v205, 0
	v_mov_b32_e32 v207, 0
	v_mov_b32_e32 v96, 0
	v_mov_b32_e32 v97, 0
	v_mov_b32_e32 v98, 0
	v_mov_b32_e32 v99, 0
	v_mov_b32_e32 v100, 0
	v_mov_b32_e32 v101, 0
	v_mov_b32_e32 v102, 0
	v_mov_b32_e32 v103, 0
	v_mov_b32_e32 v104, 0
	v_mov_b32_e32 v105, 0
	v_mov_b32_e32 v106, 0
	v_mov_b32_e32 v107, 0
	v_mov_b32_e32 v108, 0
	v_mov_b32_e32 v109, 0
	v_mov_b32_e32 v110, 0
	v_mov_b32_e32 v111, 0
	v_mov_b64_e32 v[28:29], v[12:13]
	v_mov_b64_e32 v[26:27], v[10:11]
	v_mov_b64_e32 v[24:25], v[8:9]
	v_mov_b64_e32 v[22:23], v[6:7]
	v_mov_b64_e32 v[20:21], v[4:5]
	v_mov_b64_e32 v[18:19], v[2:3]
	v_mov_b64_e32 v[16:17], v[0:1]
	v_mov_b64_e32 v[44:45], v[12:13]
	v_mov_b64_e32 v[42:43], v[10:11]
	v_mov_b64_e32 v[40:41], v[8:9]
	v_mov_b64_e32 v[38:39], v[6:7]
	v_mov_b64_e32 v[36:37], v[4:5]
	v_mov_b64_e32 v[34:35], v[2:3]
	v_mov_b64_e32 v[32:33], v[0:1]
	v_mov_b64_e32 v[60:61], v[12:13]
	v_mov_b64_e32 v[58:59], v[10:11]
	v_mov_b64_e32 v[56:57], v[8:9]
	v_mov_b64_e32 v[54:55], v[6:7]
	v_mov_b64_e32 v[52:53], v[4:5]
	v_mov_b64_e32 v[50:51], v[2:3]
	v_mov_b64_e32 v[48:49], v[0:1]
	s_mov_b32 s55, 0
	s_waitcnt vmcnt(0)
	s_mul_i32 s30, s56, 0x6400
	v_add_u32_e32 v217, s30, v246
	s_mul_i32 s30, s56, 0x4800
	v_add_u32_e32 v219, s30, v247
	s_barrier
	ds_read_b128 v[112:115], v217 offset:0
	ds_read_b128 v[116:119], v217 offset:32
	ds_read_b128 v[120:123], v217 offset:64
	ds_read_b128 v[124:127], v217 offset:96
	ds_read_b128 v[250:253], v217 offset:128
	s_waitcnt lgkmcnt(0)
	v_readfirstlane_b32 s30, v191
	s_lshr_b32 s30, s30, 8
	s_cmp_eq_u32 s30, 0
	s_cbranch_scc1 .Latt_mla_p0
	s_setprio 1
.Latt_mla_p0:
.LBB0_178:
.LBB0_191:
	s_add_i32 s30, s55, 2
	s_cmp_ge_u32 s30, s20
	s_cselect_b64 s[60:61], -1, 0
	s_cbranch_scc1 .Latt_mla_dmaend
	s_cmp_lt_u32 s55, 2
	s_cselect_b32 s62, s51, s49
	s_mul_i32 s57, s52, 0x6400
	s_add_i32 s57, s57, s42
	s_mov_b32 m0, s57
	v_mad_u32_u24 v211, s62, v237, v222
	global_load_lds_dwordx4 v211, s[2:3]
	s_add_i32 m0, s57, 0x2000
	v_mad_u32_u24 v211, s62, v239, v224
	global_load_lds_dwordx4 v211, s[2:3]
	s_add_i32 m0, s57, 0x4000
	v_mad_u32_u24 v211, s62, v241, v226
	global_load_lds_dwordx4 v211, s[2:3]
	s_ashr_i32 s63, s62, 31
	s_lshl_b64 s[30:31], s[62:63], 1
	s_mul_i32 s63, s52, 0x4800
	s_add_i32 s63, s63, s42
	s_add_i32 m0, s63, 0x12c00
	s_add_u32 s30, s21, s30
	s_addc_u32 s31, s43, s31
	global_load_lds_dwordx4 v202, s[30:31]
	s_add_i32 m0, s63, 0x14c00
	s_and_b64 vcc, exec, s[18:19]
	global_load_lds_dwordx4 v200, s[30:31]
	s_cbranch_vccz .Latt_mla_dmax
.Latt_mla_dmaend:
	v_mfma_f32_32x32x16_bf16 v[64:79], v[112:115], v[130:133], v[96:111]
	ds_read_b128 v[112:115], v217 offset:160
	v_mfma_f32_32x32x16_bf16 v[64:79], v[116:119], v[134:137], v[64:79]
	ds_read_b128 v[116:119], v217 offset:192
	v_mfma_f32_32x32x16_bf16 v[64:79], v[120:123], v[138:141], v[64:79]
	ds_read_b128 v[120:123], v217 offset:224
	v_mfma_f32_32x32x16_bf16 v[64:79], v[124:127], v[142:145], v[64:79]
	ds_read_b128 v[124:127], v217 offset:256
	v_mfma_f32_32x32x16_bf16 v[64:79], v[250:253], v[146:149], v[64:79]
	ds_read_b128 v[250:253], v217 offset:288
	s_waitcnt lgkmcnt(3)
	v_mfma_f32_32x32x16_bf16 v[64:79], v[112:115], v[150:153], v[64:79]
	ds_read_b128 v[112:115], v217 offset:320
	v_mfma_f32_32x32x16_bf16 v[64:79], v[116:119], v[154:157], v[64:79]
	ds_read_b128 v[116:119], v217 offset:352
	s_waitcnt lgkmcnt(3)
	v_mfma_f32_32x32x16_bf16 v[64:79], v[120:123], v[158:161], v[64:79]
	ds_read_b128 v[120:123], v217 offset:12800
	v_mfma_f32_32x32x16_bf16 v[64:79], v[124:127], v[162:165], v[64:79]
	ds_read_b128 v[124:127], v217 offset:12832
	s_waitcnt lgkmcnt(3)
	v_mfma_f32_32x32x16_bf16 v[64:79], v[250:253], v[166:169], v[64:79]
	ds_read_b128 v[250:253], v217 offset:12864
	v_mfma_f32_32x32x16_bf16 v[64:79], v[112:115], v[170:173], v[64:79]
	ds_read_b128 v[112:115], v217 offset:12896
	s_waitcnt lgkmcnt(3)
	v_mfma_f32_32x32x16_bf16 v[64:79], v[116:119], v[174:177], v[64:79]
	ds_read_b128 v[116:119], v217 offset:12928
	v_mfma_f32_32x32x16_bf16 v[80:95], v[120:123], v[130:133], v[96:111]
	ds_read_b128 v[120:123], v217 offset:12960
	s_waitcnt lgkmcnt(3)
	v_mfma_f32_32x32x16_bf16 v[80:95], v[124:127], v[134:137], v[80:95]
	ds_read_b128 v[124:127], v217 offset:12992
	v_mfma_f32_32x32x16_bf16 v[80:95], v[250:253], v[138:141], v[80:95]
	ds_read_b128 v[250:253], v217 offset:13024
	s_waitcnt lgkmcnt(3)
	v_mfma_f32_32x32x16_bf16 v[80:95], v[112:115], v[142:145], v[80:95]
	ds_read_b128 v[112:115], v217 offset:13056
	v_mfma_f32_32x32x16_bf16 v[80:95], v[116:119], v[146:149], v[80:95]
	ds_read_b128 v[116:119], v217 offset:13088
	v_max3_f32 v211, v64, v65, v66
	s_waitcnt lgkmcnt(3)
	v_mfma_f32_32x32x16_bf16 v[80:95], v[120:123], v[150:153], v[80:95]
	ds_read_b128 v[120:123], v217 offset:13120
	v_max3_f32 v213, v67, v68, v69
	v_mfma_f32_32x32x16_bf16 v[80:95], v[124:127], v[154:157], v[80:95]
	ds_read_b128 v[124:127], v217 offset:13152
	v_max3_f32 v211, v211, v70, v71
	s_waitcnt lgkmcnt(3)
	v_mfma_f32_32x32x16_bf16 v[80:95], v[250:253], v[158:161], v[80:95]
	v_max3_f32 v213, v213, v72, v73
	v_mfma_f32_32x32x16_bf16 v[80:95], v[112:115], v[162:165], v[80:95]
	v_max3_f32 v211, v211, v74, v75
	s_waitcnt lgkmcnt(1)
	v_mfma_f32_32x32x16_bf16 v[80:95], v[116:119], v[166:169], v[80:95]
	v_max3_f32 v213, v213, v76, v77
	v_mfma_f32_32x32x16_bf16 v[80:95], v[120:123], v[170:173], v[80:95]
	v_max3_f32 v211, v211, v78, v79
	s_waitcnt lgkmcnt(0)
	v_mfma_f32_32x32x16_bf16 v[80:95], v[124:127], v[174:177], v[80:95]
	ds_read_b128 v[112:115], v219 offset:0
	ds_read_b128 v[116:119], v219 offset:4608
	ds_read_b128 v[120:123], v219 offset:9216
	s_cmp_eq_u32 s55, 0
	s_cselect_b32 s31, 0xff7fffff, 0
	s_nop 6
	v_max3_f32 v215, v80, v81, v82
	v_max3_f32 v209, v83, v84, v85
	v_max3_f32 v215, v215, v86, v87
	v_max3_f32 v209, v209, v88, v89
	v_max3_f32 v215, v215, v90, v91
	v_max3_f32 v209, v209, v92, v93
	v_max3_f32 v215, v215, v94, v95
	v_max3_f32 v209, v209, v211, v213
	v_max_f32_e32 v209, v209, v215
	v_cmp_lt_f32_e32 vcc, s58, v209
	s_cmp_eq_u32 s55, 0
	s_cbranch_scc1 .Latt_mla_rare
	s_cbranch_vccnz .Latt_mla_rare
.Latt_mla_norescale:
	v_exp_f32_e32 v64, v64
	v_exp_f32_e32 v65, v65
	v_exp_f32_e32 v66, v66
	v_exp_f32_e32 v67, v67
	v_exp_f32_e32 v68, v68
	v_exp_f32_e32 v69, v69
	v_exp_f32_e32 v70, v70
	v_exp_f32_e32 v71, v71
	v_cvt_pk_bf16_f32 v124, v64, v65
	v_cvt_pk_bf16_f32 v125, v66, v67
	v_cvt_pk_bf16_f32 v126, v68, v69
	v_cvt_pk_bf16_f32 v127, v70, v71
	s_waitcnt lgkmcnt(1)
	s_nop 0
	v_mfma_f32_32x32x16_bf16 v[48:63], v[112:115], v[124:127], v[48:63]
	ds_read_b128 v[112:115], v219 offset:13824
	v_exp_f32_e32 v72, v72
	v_exp_f32_e32 v73, v73
	v_exp_f32_e32 v74, v74
	v_exp_f32_e32 v75, v75
	v_mfma_f32_32x32x16_bf16 v[32:47], v[116:119], v[124:127], v[32:47]
	ds_read_b128 v[116:119], v219 offset:32
	v_cvt_pk_bf16_f32 v250, v72, v73
	v_exp_f32_e32 v76, v76
	v_exp_f32_e32 v77, v77
	v_cvt_pk_bf16_f32 v251, v74, v75
	s_waitcnt lgkmcnt(1)
	v_mfma_f32_32x32x16_bf16 v[16:31], v[120:123], v[124:127], v[16:31]
	ds_read_b128 v[120:123], v219 offset:4640
	v_exp_f32_e32 v78, v78
	v_exp_f32_e32 v79, v79
	v_cvt_pk_bf16_f32 v252, v76, v77
	v_cvt_pk_bf16_f32 v253, v78, v79
	v_mfma_f32_32x32x16_bf16 v[0:15], v[112:115], v[124:127], v[0:15]
	ds_read_b128 v[112:115], v219 offset:9248
	v_add_f32_e32 v209, v64, v68
	v_add_f32_e32 v211, v65, v69
	v_add_f32_e32 v213, v66, v70
	v_add_f32_e32 v215, v67, v71
	s_waitcnt lgkmcnt(1)
	v_mfma_f32_32x32x16_bf16 v[48:63], v[116:119], v[250:253], v[48:63]
	ds_read_b128 v[64:67], v219 offset:13856
	ds_read_b128 v[68:71], v219 offset:64
	v_exp_f32_e32 v80, v80
	v_exp_f32_e32 v81, v81
	v_exp_f32_e32 v82, v82
	v_exp_f32_e32 v83, v83
	v_cvt_pk_bf16_f32 v124, v80, v81
	v_mfma_f32_32x32x16_bf16 v[32:47], v[120:123], v[250:253], v[32:47]
	ds_read_b128 v[116:119], v219 offset:4672
	ds_read_b128 v[120:123], v219 offset:9280
	v_exp_f32_e32 v84, v84
	v_exp_f32_e32 v85, v85
	v_cvt_pk_bf16_f32 v125, v82, v83
	v_exp_f32_e32 v86, v86
	v_exp_f32_e32 v87, v87
	s_waitcnt lgkmcnt(3)
	v_mfma_f32_32x32x16_bf16 v[16:31], v[112:115], v[250:253], v[16:31]
	ds_read_b128 v[112:115], v219 offset:13888
	v_cvt_pk_bf16_f32 v126, v84, v85
	v_cvt_pk_bf16_f32 v127, v86, v87
	v_add_f32_e32 v209, v209, v72
	v_add_f32_e32 v211, v211, v73
	v_add_f32_e32 v213, v213, v74
	v_mfma_f32_32x32x16_bf16 v[0:15], v[64:67], v[250:253], v[0:15]
	ds_read_b128 v[64:67], v219 offset:96
	v_add_f32_e32 v215, v215, v75
	v_add_f32_e32 v209, v209, v76
	v_add_f32_e32 v211, v211, v77
	v_add_f32_e32 v213, v213, v78
	v_add_f32_e32 v215, v215, v79
	s_waitcnt lgkmcnt(3)
	v_mfma_f32_32x32x16_bf16 v[48:63], v[68:71], v[124:127], v[48:63]
	ds_read_b128 v[72:75], v219 offset:4704
	ds_read_b128 v[76:79], v219 offset:9312
	v_exp_f32_e32 v88, v88
	v_exp_f32_e32 v89, v89
	v_exp_f32_e32 v90, v90
	v_exp_f32_e32 v91, v91
	v_cvt_pk_bf16_f32 v250, v88, v89
	v_mfma_f32_32x32x16_bf16 v[32:47], v[116:119], v[124:127], v[32:47]
	ds_read_b128 v[68:71], v219 offset:13920
	v_exp_f32_e32 v92, v92
	v_exp_f32_e32 v93, v93
	v_cvt_pk_bf16_f32 v251, v90, v91
	v_exp_f32_e32 v94, v94
	v_exp_f32_e32 v95, v95
	s_waitcnt lgkmcnt(4)
	v_mfma_f32_32x32x16_bf16 v[16:31], v[120:123], v[124:127], v[16:31]
	v_cvt_pk_bf16_f32 v252, v92, v93
	v_cvt_pk_bf16_f32 v253, v94, v95
	v_add_f32_e32 v209, v209, v80
	v_add_f32_e32 v211, v211, v81
	v_add_f32_e32 v213, v213, v82
	v_mfma_f32_32x32x16_bf16 v[0:15], v[112:115], v[124:127], v[0:15]
	v_add_f32_e32 v215, v215, v83
	v_add_f32_e32 v209, v209, v84
	v_add_f32_e32 v211, v211, v85
	v_add_f32_e32 v213, v213, v86
	v_add_f32_e32 v215, v215, v87
	s_waitcnt lgkmcnt(2)
	v_mfma_f32_32x32x16_bf16 v[48:63], v[64:67], v[250:253], v[48:63]
	s_mul_i32 s30, s53, 0x6400
	v_add_u32_e32 v217, s30, v246
	ds_read_b128 v[112:115], v217 offset:0
	v_add_f32_e32 v209, v209, v88
	v_add_f32_e32 v211, v211, v89
	v_mfma_f32_32x32x16_bf16 v[32:47], v[72:75], v[250:253], v[32:47]
	ds_read_b128 v[116:119], v217 offset:32
	v_add_f32_e32 v213, v213, v90
	v_add_f32_e32 v215, v215, v91
	s_waitcnt lgkmcnt(2)
	v_mfma_f32_32x32x16_bf16 v[16:31], v[76:79], v[250:253], v[16:31]
	ds_read_b128 v[120:123], v217 offset:64
	v_add_f32_e32 v209, v209, v92
	v_add_f32_e32 v211, v211, v93
	v_mfma_f32_32x32x16_bf16 v[0:15], v[68:71], v[250:253], v[0:15]
	ds_read_b128 v[124:127], v217 offset:96
	v_add_f32_e32 v213, v213, v94
	v_add_f32_e32 v215, v215, v95
	ds_read_b128 v[250:253], v217 offset:128
	v_add_f32_e32 v209, v209, v211
	v_add_f32_e32 v213, v213, v215
	v_add_f32_e32 v209, v209, v213
	v_add_f32_e32 v205, v205, v209
.Latt_mla_skip:
	s_waitcnt vmcnt(0)
	s_add_i32 s30, s52, 1
	s_cmp_lg_u32 s52, 2
	s_cselect_b32 s57, s30, 0
	s_add_i32 s55, s55, 1
	s_add_i32 s49, s49, 64
	s_add_i32 s51, s51, 64
	s_mov_b32 s56, s53
	s_mov_b32 s53, s52
	s_mov_b32 s52, s57
	s_mul_i32 s30, s56, 0x4800
	v_add_u32_e32 v219, s30, v247
	s_cmp_eq_u32 s20, s55
	s_waitcnt lgkmcnt(0)
	s_barrier
	s_cbranch_scc0 .LBB0_178
	s_branch .LBB0_153
.Latt_mla_dmax:
	s_add_i32 m0, s63, 0x16c00
	s_and_b64 vcc, exec, s[12:13]
	global_load_lds_dwordx4 v198, s[30:31]
	s_cbranch_vccnz .Latt_mla_dmaend
	s_add_i32 m0, s57, 0x6000
	v_mad_u32_u24 v211, s62, v243, v228
	global_load_lds_dwordx4 v211, s[2:3]
	s_branch .Latt_mla_dmaend
